# v43 + L2 warm-up helper skipped in the three phases whose tail round hosts pre-run units (5, 10, 26)
# speedup vs baseline: 1.0045x; 1.0038x over previous
;     __host__ __device__ bool next(int i, Unit& u) const {
;         const long L = (long)i * G + c; if (L >= nwg) return false;
;         int wgid = (int)L; { const int q = nwg / NXCD, r = nwg % NXCD, xcd = wgid % NXCD, off = wgid / NXCD; wgid = (xcd < r ? xcd * (q + 1) : r * (q + 1) + (xcd - r) * q) + off; }
;         const int nig = WGM * nN, gid = wgid / nig, fm = gid * WGM, gsz = (nM - fm) < WGM ? (nM - fm) : WGM;
;         u.pm = fm + ((wgid % nig) % gsz); u.pn = (wgid % nig) / gsz; return true;
;     }
.LBB0_661:
	s_waitcnt vmcnt(0)
	s_cmp_lg_u32 s94, 0x100
	s_cbranch_scc1 .Lwarm_done
	s_cmp_eq_u32 s83, 5
	s_cbranch_scc1 .Lwarm_done
	s_cmp_eq_u32 s83, 10
	s_cbranch_scc1 .Lwarm_done
	s_cmp_eq_u32 s83, 26
	s_cbranch_scc1 .Lwarm_done
	s_and_b32 s78, s20, 0xff
	s_and_b32 s79, s96, 7
	s_cmp_ge_u32 s79, s78
	s_cbranch_scc1 .Lwarm_done
	s_lshr_b32 s80, s96, 3
	s_add_i32 s80, s80, -1
	s_cmp_gt_u32 s80, 7
	s_cbranch_scc1 .Lwarm_done
	s_lshr_b32 s81, s20, 3
	s_and_b32 s54, s20, 7
	s_mul_i32 s55, s79, s81
	s_min_u32 s54, s79, s54
	s_add_i32 s55, s55, s54
	s_lshr_b32 s54, s20, 8
	s_lshl_b32 s54, s54, 5
	s_add_i32 s55, s55, s54
	s_lshr_b32 s54, s55, 5
	s_and_b32 s55, s55, 31
	s_lshl_b32 s54, s54, 3
	s_sub_i32 s62, s60, s54
	s_min_i32 s62, s62, 8
	s_ff1_i32_b32 s63, s62
	s_lshr_b32 s64, s55, s63
	s_add_i32 s62, s62, -1
	s_and_b32 s55, s55, s62
	s_add_i32 s54, s54, s55
	s_lshr_b32 s65, s42, 3
	s_mul_i32 s55, s65, s80
	s_mul_i32 s62, s42, s54
	s_mul_hi_u32 s63, s42, s54
	s_mul_i32 s81, s43, s54
	s_add_i32 s63, s63, s81
	s_add_u32 s62, s62, s18
	s_addc_u32 s63, s63, s19
	s_add_u32 s62, s62, s55
	s_addc_u32 s63, s63, 0
	s_mul_i32 s68, s42, s64
	s_mul_hi_u32 s69, s42, s64
	s_mul_i32 s81, s43, s64
	s_add_i32 s69, s69, s81
	s_add_u32 s68, s68, s8
	s_addc_u32 s69, s69, s9
	s_add_u32 s68, s68, s55
	s_addc_u32 s69, s69, 0
	v_mbcnt_lo_u32_b32 v2, -1, 0
	v_mbcnt_hi_u32_b32 v2, -1, v2
	v_add_u32_e32 v2, s84, v2
	v_lshlrev_b32_e32 v2, 4, v2
	s_lshr_b32 s54, s65, 13
